# WPA/WPR/WOUT weight conversions deferred from P0 to the end of P1 (before its grid barrier), registers renamed into dead ranges
# speedup vs baseline: 1.0028x; 1.0028x over previous
; __global__ void __launch_bounds__(512, 2) fwd_megakernel(Args a) {
;     ...
;     conv_mat<0>(a.in[I_WIN], a.in[I_MIXN], DM, 11264, WIN, scr, gw, NGW, lane);
;     conv_mat<0>(a.in[I_WPA], nullptr, 1024, DM, WPA, scr, gw, NGW, lane);
;     conv_mat<0>(a.in[I_WPR], nullptr, 1024, DM, WPR, scr, gw, NGW, lane);
;     conv_mat<0>(a.in[I_WOUT], nullptr, DM, DM, WWO, scr, gw, NGW, lane);
.LBB0_47:
	s_load_dwordx16 s[36:51], s[0:1], 0x40
	s_add_u32 s0, s62, 0x7300000
	s_addc_u32 s1, s63, 0
	s_waitcnt lgkmcnt(0)
	v_writelane_b32 v250, s36, 12
	s_nop 1
	v_writelane_b32 v250, s37, 13
	v_writelane_b32 v250, s38, 14
	v_writelane_b32 v250, s39, 15
	v_writelane_b32 v250, s40, 16
	v_writelane_b32 v250, s41, 17
	v_writelane_b32 v250, s42, 18
	v_writelane_b32 v250, s43, 19
	v_writelane_b32 v250, s44, 20
	v_writelane_b32 v250, s45, 21
	v_writelane_b32 v250, s46, 22
	v_writelane_b32 v250, s47, 23
	v_writelane_b32 v250, s48, 24
	v_writelane_b32 v250, s49, 25
	v_writelane_b32 v250, s50, 26
	v_writelane_b32 v250, s51, 27
	v_writelane_b32 v250, s0, 28
	s_nop 1
	v_writelane_b32 v250, s1, 29
	s_add_u32 s0, s62, 0x6f00000
	s_addc_u32 s1, s63, 0
	v_writelane_b32 v250, s0, 30
	s_nop 0
	v_writelane_b32 v250, s1, 31

; #define LAS __attribute__((address_space(3)))
; __device__ __forceinline__ unsigned pkbf(float lo, float hi) { const f32x2_m v = {lo, hi}; const bf16x2_m b = __builtin_convertvector(v, bf16x2_m); return __builtin_bit_cast(unsigned, b); }
; __device__ __forceinline__ void tr_item(const float* W, const float* nw, int K, int N, bf16* WT, int k0, int n0, int drow0, LAS float* scr, int lane) {
;     { const int r = lane >> 3, c4 = lane & 7; f32x4 v[8];
; #pragma unroll
;       for (int i = 0; i < 8; ++i) v[i] = *(const f32x4*)(W + (size_t)(k0 + 8 * i + r) * N + n0 + 4 * c4);
; #pragma unroll
;       for (int i = 0; i < 8; ++i) { LAS float* d = scr + (8 * i + r) * 33 + 4 * c4; const float s = nw ? nw[k0 + 8 * i + r] : 1.f; d[0] = v[i].x * s; d[1] = v[i].y * s; d[2] = v[i].z * s; d[3] = v[i].w * s; } }
;     asm volatile("s_waitcnt lgkmcnt(0)" ::: "memory");
;     const int c = lane & 7;
; #pragma unroll
;     for (int j = 0; j < 4; ++j) { const int n = (lane >> 3) + 8 * j; const LAS float* s = scr + (8 * c) * 33 + n;
;         v4u o; o.x = pkbf(s[0 * 33], s[1 * 33]); o.y = pkbf(s[2 * 33], s[3 * 33]); o.z = pkbf(s[4 * 33], s[5 * 33]); o.w = pkbf(s[6 * 33], s[7 * 33]);
;         *(v4u*)(WT + (size_t)(drow0 + n) * K + k0 + 8 * c) = o; }
;     asm volatile("s_waitcnt lgkmcnt(0)" ::: "memory");
; }
; template <int MODE> __device__ __forceinline__ void conv_mat(const float* W, const float* nw, int K, int N, bf16* WT, LAS float* scr, int gw, int NGW, int lane) {
;     const int nblk = N / 32, nitems = (K / 64) * nblk;
;     for (int it = gw; it < nitems; it += NGW) { const int kb = it / nblk, nb = it % nblk, n0 = 32 * nb; int d = n0;
;         if (MODE == 1) { d = (n0 < DFF) ? 256 * (n0 / 128) + (n0 % 128) : 256 * ((n0 - DFF) / 128) + 128 + ((n0 - DFF) % 128); }
;         tr_item(W, nw, K, N, WT, 64 * kb, n0, d, scr, lane); }
; __global__ void __launch_bounds__(512, 2) fwd_megakernel(Args a) {
;     ...
;     conv_mat<0>(a.in[I_WPA], nullptr, 1024, DM, WPA, scr, gw, NGW, lane);
.LBB0_102:
	s_cmpk_gt_i32 s34, 0x3ff
	s_cbranch_scc1 .LBB0_52
	v_lshlrev_b32_e32 v152, 4, v225
	v_readlane_b32 s0, v250, 3
	v_mul_u32_u24_e32 v149, 0x84, v224
	v_add_u32_e32 v147, s0, v152
	v_mul_u32_u24_e32 v145, 0x420, v225
	v_readlane_b32 s72, v250, 30
	v_lshlrev_b32_e32 v154, 2, v224
	v_mov_b32_e32 v153, 0
	v_readlane_b32 s74, v250, 22
	v_readlane_b32 s75, v250, 23
	v_readlane_b32 s73, v250, 31
	v_add3_u32 v145, s0, v145, v154
	s_lshl_b32 s3, s34, 5
	v_add_u32_e32 v154, v147, v149
	v_lshlrev_b32_e32 v146, 2, v225
	v_lshl_add_u64 v[150:151], s[74:75], 0, v[152:153]
	v_lshlrev_b32_e32 v148, 3, v225
	v_lshl_add_u64 v[152:153], s[72:73], 0, v[152:153]
	s_lshl_b32 s6, s64, 5
	v_add_u32_e32 v147, 0x420, v154
	v_add_u32_e32 v149, 0x428, v154
	v_add_u32_e32 v155, 0x840, v154
	v_add_u32_e32 v156, 0x848, v154
	v_add_u32_e32 v157, 0xc60, v154
	v_add_u32_e32 v158, 0xc68, v154
	v_add_u32_e32 v159, 0x1080, v154
	v_add_u32_e32 v160, 0x1088, v154
	v_add_u32_e32 v161, 0x14a0, v154
	v_add_u32_e32 v162, 0x14a8, v154
	v_add_u32_e32 v163, 0x18c0, v154
	v_add_u32_e32 v164, 0x18c8, v154
	v_add_u32_e32 v165, 0x1ce0, v154
	v_add_u32_e32 v166, 0x1ce8, v154
	s_mov_b32 s7, s3
	s_mov_b32 s8, s34
	v_readlane_b32 s76, v250, 24
	v_readlane_b32 s77, v250, 25
	v_readlane_b32 s78, v250, 26
	v_readlane_b32 s79, v250, 27
.LBB0_49:
	s_ashr_i32 s0, s8, 31
	s_lshr_b32 s0, s0, 26
	s_add_i32 s0, s8, s0
	s_lshl_b32 s1, s0, 5
	s_andn2_b32 s0, s0, 63
	s_and_b32 s1, s1, 0xfffff800
	v_or_b32_e32 v168, s0, v224
	s_sub_i32 s72, s7, s1
	v_or_b32_e32 v170, 8, v168
	v_or_b32_e32 v172, 16, v168
	v_or_b32_e32 v174, 24, v168
	v_or_b32_e32 v180, 40, v168
	v_or_b32_e32 v182, 48, v168
	v_or_b32_e32 v184, 56, v168
	v_ashrrev_i32_e32 v169, 31, v168
	v_or_b32_e32 v176, 32, v168
	s_ashr_i32 s73, s72, 31
	v_ashrrev_i32_e32 v171, 31, v170
	v_ashrrev_i32_e32 v173, 31, v172
	v_ashrrev_i32_e32 v175, 31, v174
	v_ashrrev_i32_e32 v181, 31, v180
	v_ashrrev_i32_e32 v183, 31, v182
	v_ashrrev_i32_e32 v185, 31, v184
	v_lshlrev_b64 v[168:169], 13, v[168:169]
	v_ashrrev_i32_e32 v177, 31, v176
	v_lshl_add_u64 v[186:187], s[72:73], 2, v[150:151]
	v_lshlrev_b64 v[170:171], 13, v[170:171]
	v_lshlrev_b64 v[172:173], 13, v[172:173]
	v_lshlrev_b64 v[174:175], 13, v[174:175]
	v_lshlrev_b64 v[180:181], 13, v[180:181]
	v_lshlrev_b64 v[182:183], 13, v[182:183]
	v_lshlrev_b64 v[184:185], 13, v[184:185]
	v_lshlrev_b64 v[176:177], 13, v[176:177]
	v_lshl_add_u64 v[168:169], v[186:187], 0, v[168:169]
	v_lshl_add_u64 v[188:189], v[186:187], 0, v[170:171]
	v_lshl_add_u64 v[190:191], v[186:187], 0, v[172:173]
	v_lshl_add_u64 v[192:193], v[186:187], 0, v[174:175]
	v_lshl_add_u64 v[194:195], v[186:187], 0, v[180:181]
	v_lshl_add_u64 v[196:197], v[186:187], 0, v[182:183]
	v_lshl_add_u64 v[200:201], v[186:187], 0, v[184:185]
	v_lshl_add_u64 v[176:177], v[186:187], 0, v[176:177]
	global_load_dwordx4 v[168:171], v[168:169], off nt
	s_nop 0
	global_load_dwordx4 v[172:175], v[188:189], off nt
	global_load_dwordx4 v[180:183], v[190:191], off nt
	global_load_dwordx4 v[184:187], v[192:193], off nt
	s_nop 0
	global_load_dwordx4 v[188:191], v[176:177], off nt
	s_nop 0
	global_load_dwordx4 v[192:195], v[194:195], off nt
	s_nop 0
	global_load_dwordx4 v[196:199], v[196:197], off nt
	s_nop 0
	global_load_dwordx4 v[200:203], v[200:201], off nt
	v_add_u32_e32 v204, s72, v224
	v_add_u32_e32 v206, 8, v204
	v_add_u32_e32 v208, 16, v204
	v_add_u32_e32 v210, 24, v204
	s_ashr_i32 s1, s0, 31
	v_ashrrev_i32_e32 v205, 31, v204
	v_ashrrev_i32_e32 v207, 31, v206
	v_ashrrev_i32_e32 v209, 31, v208
	v_ashrrev_i32_e32 v211, 31, v210
	v_lshl_add_u64 v[176:177], s[0:1], 1, v[152:153]
	v_lshlrev_b64 v[204:205], 11, v[204:205]
	v_lshlrev_b64 v[206:207], 11, v[206:207]
	v_lshlrev_b64 v[208:209], 11, v[208:209]
	v_lshlrev_b64 v[210:211], 11, v[210:211]
	v_lshl_add_u64 v[204:205], v[176:177], 0, v[204:205]
	v_lshl_add_u64 v[206:207], v[176:177], 0, v[206:207]
	v_lshl_add_u64 v[208:209], v[176:177], 0, v[208:209]
	v_lshl_add_u64 v[176:177], v[176:177], 0, v[210:211]
	s_add_i32 s8, s8, s64
	s_add_i32 s7, s7, s6
	s_cmpk_lt_i32 s8, 0x400
	s_waitcnt vmcnt(7)
	ds_write2_b32 v154, v168, v169 offset1:1
	ds_write2_b32 v154, v170, v171 offset0:2 offset1:3
	s_waitcnt vmcnt(6)
	ds_write2_b32 v147, v172, v173 offset1:1
	ds_write2_b32 v149, v174, v175 offset1:1
	s_waitcnt vmcnt(5)
	ds_write2_b32 v155, v180, v181 offset1:1
	ds_write2_b32 v156, v182, v183 offset1:1
	s_waitcnt vmcnt(4)
	ds_write2_b32 v157, v184, v185 offset1:1
	ds_write2_b32 v158, v186, v187 offset1:1
	s_waitcnt vmcnt(3)
	ds_write2_b32 v159, v188, v189 offset1:1
	ds_write2_b32 v160, v190, v191 offset1:1
	s_waitcnt vmcnt(2)
	ds_write2_b32 v161, v192, v193 offset1:1
	ds_write2_b32 v162, v194, v195 offset1:1
	s_waitcnt vmcnt(1)
	ds_write2_b32 v163, v196, v197 offset1:1
	ds_write2_b32 v164, v198, v199 offset1:1
	s_waitcnt vmcnt(0)
	ds_write2_b32 v165, v200, v201 offset1:1
	ds_write2_b32 v166, v202, v203 offset1:1
	s_waitcnt lgkmcnt(0)
	ds_read2_b32 v[172:173], v145 offset0:33 offset1:41
	ds_read2_b32 v[174:175], v145 offset1:8
	ds_read2_b32 v[180:181], v145 offset0:66 offset1:74
	ds_read2_b32 v[182:183], v145 offset0:99 offset1:107
	ds_read2_b32 v[184:185], v145 offset0:132 offset1:140
	ds_read2_b32 v[186:187], v145 offset0:165 offset1:173
	ds_read2_b32 v[188:189], v145 offset0:198 offset1:206
	ds_read2_b32 v[190:191], v145 offset0:231 offset1:239
	ds_read2_b32 v[192:193], v145 offset0:49 offset1:57
	ds_read2_b32 v[194:195], v145 offset0:16 offset1:24
	ds_read2_b32 v[196:197], v145 offset0:82 offset1:90
	ds_read2_b32 v[198:199], v145 offset0:115 offset1:123
	ds_read2_b32 v[200:201], v145 offset0:148 offset1:156
	ds_read2_b32 v[202:203], v145 offset0:181 offset1:189
	ds_read2_b32 v[210:211], v145 offset0:214 offset1:222
	ds_read2_b32 v[212:213], v145 offset0:247 offset1:255
	s_waitcnt lgkmcnt(14)
	v_cvt_pk_bf16_f32 v168, v174, v172
	s_waitcnt lgkmcnt(12)
	v_cvt_pk_bf16_f32 v169, v180, v182
	s_waitcnt lgkmcnt(10)
	v_cvt_pk_bf16_f32 v170, v184, v186
	s_waitcnt lgkmcnt(8)
	v_cvt_pk_bf16_f32 v171, v188, v190
	v_cvt_pk_bf16_f32 v172, v175, v173
	v_cvt_pk_bf16_f32 v173, v181, v183
	v_cvt_pk_bf16_f32 v174, v185, v187
	v_cvt_pk_bf16_f32 v175, v189, v191
	s_waitcnt lgkmcnt(6)
	v_cvt_pk_bf16_f32 v180, v194, v192
	s_waitcnt lgkmcnt(4)
	v_cvt_pk_bf16_f32 v181, v196, v198
	s_waitcnt lgkmcnt(2)
	v_cvt_pk_bf16_f32 v182, v200, v202
	s_waitcnt lgkmcnt(0)
	v_cvt_pk_bf16_f32 v183, v210, v212
	v_cvt_pk_bf16_f32 v184, v195, v193
	v_cvt_pk_bf16_f32 v185, v197, v199
	v_cvt_pk_bf16_f32 v186, v201, v203
	v_cvt_pk_bf16_f32 v187, v211, v213
	global_store_dwordx4 v[204:205], v[168:171], off
	global_store_dwordx4 v[206:207], v[172:175], off
	global_store_dwordx4 v[208:209], v[180:183], off
	global_store_dwordx4 v[176:177], v[184:187], off
	s_waitcnt lgkmcnt(0)
	s_cbranch_scc1 .LBB0_49
; #define LAS __attribute__((address_space(3)))
; __device__ __forceinline__ unsigned pkbf(float lo, float hi) { const f32x2_m v = {lo, hi}; const bf16x2_m b = __builtin_convertvector(v, bf16x2_m); return __builtin_bit_cast(unsigned, b); }
; __device__ __forceinline__ void tr_item(const float* W, const float* nw, int K, int N, bf16* WT, int k0, int n0, int drow0, LAS float* scr, int lane) {
;     { const int r = lane >> 3, c4 = lane & 7; f32x4 v[8];
; #pragma unroll
;       for (int i = 0; i < 8; ++i) v[i] = *(const f32x4*)(W + (size_t)(k0 + 8 * i + r) * N + n0 + 4 * c4);
; #pragma unroll
;       for (int i = 0; i < 8; ++i) { LAS float* d = scr + (8 * i + r) * 33 + 4 * c4; const float s = nw ? nw[k0 + 8 * i + r] : 1.f; d[0] = v[i].x * s; d[1] = v[i].y * s; d[2] = v[i].z * s; d[3] = v[i].w * s; } }
;     asm volatile("s_waitcnt lgkmcnt(0)" ::: "memory");
;     const int c = lane & 7;
; #pragma unroll
;     for (int j = 0; j < 4; ++j) { const int n = (lane >> 3) + 8 * j; const LAS float* s = scr + (8 * c) * 33 + n;
;         v4u o; o.x = pkbf(s[0 * 33], s[1 * 33]); o.y = pkbf(s[2 * 33], s[3 * 33]); o.z = pkbf(s[4 * 33], s[5 * 33]); o.w = pkbf(s[6 * 33], s[7 * 33]);
;         *(v4u*)(WT + (size_t)(drow0 + n) * K + k0 + 8 * c) = o; }
;     asm volatile("s_waitcnt lgkmcnt(0)" ::: "memory");
; }
; template <int MODE> __device__ __forceinline__ void conv_mat(const float* W, const float* nw, int K, int N, bf16* WT, LAS float* scr, int gw, int NGW, int lane) {
;     const int nblk = N / 32, nitems = (K / 64) * nblk;
;     for (int it = gw; it < nitems; it += NGW) { const int kb = it / nblk, nb = it % nblk, n0 = 32 * nb; int d = n0;
;         if (MODE == 1) { d = (n0 < DFF) ? 256 * (n0 / 128) + (n0 % 128) : 256 * ((n0 - DFF) / 128) + 128 + ((n0 - DFF) % 128); }
;         tr_item(W, nw, K, N, WT, 64 * kb, n0, d, scr, lane); }
; __global__ void __launch_bounds__(512, 2) fwd_megakernel(Args a) {
;     ...
;     conv_mat<0>(a.in[I_WPR], nullptr, 1024, DM, WPR, scr, gw, NGW, lane);
	v_lshlrev_b32_e32 v150, 2, v146
	v_mov_b32_e32 v151, 0
	v_readlane_b32 s76, v250, 24
	v_readlane_b32 s77, v250, 25
	v_readlane_b32 s0, v250, 28
	v_readlane_b32 s1, v250, 29
	v_lshl_add_u64 v[146:147], s[76:77], 0, v[150:151]
	v_lshlrev_b32_e32 v150, 1, v148
	v_lshl_add_u64 v[148:149], s[0:1], 0, v[150:151]
	s_mov_b32 s7, s34
	v_readlane_b32 s74, v250, 22
	v_readlane_b32 s75, v250, 23
	v_readlane_b32 s78, v250, 26
	v_readlane_b32 s79, v250, 27
.LBB0_51:
	s_ashr_i32 s0, s7, 31
	s_lshr_b32 s0, s0, 26
	s_add_i32 s0, s7, s0
	s_lshl_b32 s1, s0, 5
	s_andn2_b32 s0, s0, 63
	s_and_b32 s1, s1, 0xfffff800
	v_or_b32_e32 v150, s0, v224
	s_sub_i32 s72, s3, s1
	v_or_b32_e32 v152, 8, v150
	v_or_b32_e32 v156, 16, v150
	v_or_b32_e32 v158, 24, v150
	v_or_b32_e32 v162, 40, v150
	v_or_b32_e32 v164, 48, v150
	v_or_b32_e32 v166, 56, v150
	v_ashrrev_i32_e32 v151, 31, v150
	v_or_b32_e32 v160, 32, v150
	s_ashr_i32 s73, s72, 31
	v_ashrrev_i32_e32 v153, 31, v152
	v_ashrrev_i32_e32 v157, 31, v156
	v_ashrrev_i32_e32 v159, 31, v158
	v_ashrrev_i32_e32 v163, 31, v162
	v_ashrrev_i32_e32 v165, 31, v164
	v_ashrrev_i32_e32 v167, 31, v166
	v_lshlrev_b64 v[150:151], 13, v[150:151]
	v_ashrrev_i32_e32 v161, 31, v160
	v_lshl_add_u64 v[168:169], s[72:73], 2, v[146:147]
	v_lshlrev_b64 v[152:153], 13, v[152:153]
	v_lshlrev_b64 v[156:157], 13, v[156:157]
	v_lshlrev_b64 v[158:159], 13, v[158:159]
	v_lshlrev_b64 v[162:163], 13, v[162:163]
	v_lshlrev_b64 v[164:165], 13, v[164:165]
	v_lshlrev_b64 v[166:167], 13, v[166:167]
	v_lshlrev_b64 v[160:161], 13, v[160:161]
	v_lshl_add_u64 v[150:151], v[168:169], 0, v[150:151]
	v_lshl_add_u64 v[170:171], v[168:169], 0, v[152:153]
	v_lshl_add_u64 v[172:173], v[168:169], 0, v[156:157]
	v_lshl_add_u64 v[174:175], v[168:169], 0, v[158:159]
	v_lshl_add_u64 v[180:181], v[168:169], 0, v[162:163]
	v_lshl_add_u64 v[182:183], v[168:169], 0, v[164:165]
	v_lshl_add_u64 v[184:185], v[168:169], 0, v[166:167]
	v_lshl_add_u64 v[176:177], v[168:169], 0, v[160:161]
	global_load_dwordx4 v[150:153], v[150:151], off nt
	s_nop 0
	global_load_dwordx4 v[156:159], v[170:171], off nt
	global_load_dwordx4 v[160:163], v[172:173], off nt
	global_load_dwordx4 v[164:167], v[174:175], off nt
	s_nop 0
	global_load_dwordx4 v[168:171], v[176:177], off nt
	global_load_dwordx4 v[172:175], v[180:181], off nt
	s_nop 0
	global_load_dwordx4 v[180:183], v[182:183], off nt
	s_nop 0
	global_load_dwordx4 v[184:187], v[184:185], off nt
	v_add_u32_e32 v188, s72, v224
	v_add_u32_e32 v190, 8, v188
	v_add_u32_e32 v192, 16, v188
	v_add_u32_e32 v194, 24, v188
	v_add_u32_e32 v155, 0x420, v154
	v_add_u32_e32 v179, 0x428, v154
	v_add_u32_e32 v196, 0x840, v154
	v_add_u32_e32 v197, 0x848, v154
	v_add_u32_e32 v198, 0xc60, v154
	v_add_u32_e32 v199, 0xc68, v154
	v_add_u32_e32 v200, 0x1080, v154
	v_add_u32_e32 v201, 0x1088, v154
	v_add_u32_e32 v202, 0x14a0, v154
	v_add_u32_e32 v203, 0x14a8, v154
	v_add_u32_e32 v204, 0x18c0, v154
	v_add_u32_e32 v205, 0x18c8, v154
	v_add_u32_e32 v206, 0x1ce0, v154
	v_add_u32_e32 v207, 0x1ce8, v154
	s_ashr_i32 s1, s0, 31
	v_ashrrev_i32_e32 v189, 31, v188
	v_ashrrev_i32_e32 v191, 31, v190
	v_ashrrev_i32_e32 v193, 31, v192
	v_ashrrev_i32_e32 v195, 31, v194
	v_lshl_add_u64 v[176:177], s[0:1], 1, v[148:149]
	v_lshlrev_b64 v[188:189], 11, v[188:189]
	v_lshlrev_b64 v[190:191], 11, v[190:191]
	v_lshlrev_b64 v[192:193], 11, v[192:193]
	v_lshlrev_b64 v[194:195], 11, v[194:195]
	v_lshl_add_u64 v[188:189], v[176:177], 0, v[188:189]
	v_lshl_add_u64 v[190:191], v[176:177], 0, v[190:191]
	v_lshl_add_u64 v[192:193], v[176:177], 0, v[192:193]
	v_lshl_add_u64 v[176:177], v[176:177], 0, v[194:195]
	s_add_i32 s7, s7, s64
	s_add_i32 s3, s3, s6
	s_cmpk_lt_i32 s7, 0x400
	s_waitcnt vmcnt(7)
	ds_write2_b32 v154, v150, v151 offset1:1
	ds_write2_b32 v154, v152, v153 offset0:2 offset1:3
	s_waitcnt vmcnt(6)
	ds_write2_b32 v155, v156, v157 offset1:1
	ds_write2_b32 v179, v158, v159 offset1:1
	s_waitcnt vmcnt(5)
	ds_write2_b32 v196, v160, v161 offset1:1
	ds_write2_b32 v197, v162, v163 offset1:1
	s_waitcnt vmcnt(4)
	ds_write2_b32 v198, v164, v165 offset1:1
	ds_write2_b32 v199, v166, v167 offset1:1
	s_waitcnt vmcnt(3)
	ds_write2_b32 v200, v168, v169 offset1:1
	ds_write2_b32 v201, v170, v171 offset1:1
	s_waitcnt vmcnt(2)
	ds_write2_b32 v202, v172, v173 offset1:1
	ds_write2_b32 v203, v174, v175 offset1:1
	s_waitcnt vmcnt(1)
	ds_write2_b32 v204, v180, v181 offset1:1
	ds_write2_b32 v205, v182, v183 offset1:1
	s_waitcnt vmcnt(0)
	ds_write2_b32 v206, v184, v185 offset1:1
	ds_write2_b32 v207, v186, v187 offset1:1
	s_waitcnt lgkmcnt(0)
	ds_read2_b32 v[156:157], v145 offset0:33 offset1:41
	ds_read2_b32 v[158:159], v145 offset1:8
	ds_read2_b32 v[160:161], v145 offset0:66 offset1:74
	ds_read2_b32 v[162:163], v145 offset0:99 offset1:107
	ds_read2_b32 v[164:165], v145 offset0:132 offset1:140
	ds_read2_b32 v[166:167], v145 offset0:165 offset1:173
	ds_read2_b32 v[168:169], v145 offset0:198 offset1:206
	ds_read2_b32 v[170:171], v145 offset0:231 offset1:239
	ds_read2_b32 v[172:173], v145 offset0:49 offset1:57
	ds_read2_b32 v[174:175], v145 offset0:16 offset1:24
	ds_read2_b32 v[180:181], v145 offset0:82 offset1:90
	ds_read2_b32 v[182:183], v145 offset0:115 offset1:123
	ds_read2_b32 v[184:185], v145 offset0:148 offset1:156
	ds_read2_b32 v[186:187], v145 offset0:181 offset1:189
	ds_read2_b32 v[194:195], v145 offset0:214 offset1:222
	ds_read2_b32 v[196:197], v145 offset0:247 offset1:255
	s_waitcnt lgkmcnt(14)
	v_cvt_pk_bf16_f32 v150, v158, v156
	s_waitcnt lgkmcnt(12)
	v_cvt_pk_bf16_f32 v151, v160, v162
	s_waitcnt lgkmcnt(10)
	v_cvt_pk_bf16_f32 v152, v164, v166
	s_waitcnt lgkmcnt(8)
	v_cvt_pk_bf16_f32 v153, v168, v170
	v_cvt_pk_bf16_f32 v156, v159, v157
	v_cvt_pk_bf16_f32 v157, v161, v163
	v_cvt_pk_bf16_f32 v158, v165, v167
	v_cvt_pk_bf16_f32 v159, v169, v171
	s_waitcnt lgkmcnt(6)
	v_cvt_pk_bf16_f32 v160, v174, v172
	s_waitcnt lgkmcnt(4)
	v_cvt_pk_bf16_f32 v161, v180, v182
	s_waitcnt lgkmcnt(2)
	v_cvt_pk_bf16_f32 v162, v184, v186
	s_waitcnt lgkmcnt(0)
	v_cvt_pk_bf16_f32 v163, v194, v196
	v_cvt_pk_bf16_f32 v164, v175, v173
	v_cvt_pk_bf16_f32 v165, v181, v183
	v_cvt_pk_bf16_f32 v166, v185, v187
	v_cvt_pk_bf16_f32 v167, v195, v197
	global_store_dwordx4 v[188:189], v[150:153], off
	global_store_dwordx4 v[190:191], v[156:159], off
	global_store_dwordx4 v[192:193], v[160:163], off
	global_store_dwordx4 v[176:177], v[164:167], off
	s_waitcnt lgkmcnt(0)
	s_cbranch_scc1 .LBB0_51
; #define LAS __attribute__((address_space(3)))
; __device__ __forceinline__ unsigned pkbf(float lo, float hi) { const f32x2_m v = {lo, hi}; const bf16x2_m b = __builtin_convertvector(v, bf16x2_m); return __builtin_bit_cast(unsigned, b); }
; __device__ __forceinline__ void tr_item(const float* W, const float* nw, int K, int N, bf16* WT, int k0, int n0, int drow0, LAS float* scr, int lane) {
;     { const int r = lane >> 3, c4 = lane & 7; f32x4 v[8];
; #pragma unroll
;       for (int i = 0; i < 8; ++i) v[i] = *(const f32x4*)(W + (size_t)(k0 + 8 * i + r) * N + n0 + 4 * c4);
; #pragma unroll
;       for (int i = 0; i < 8; ++i) { LAS float* d = scr + (8 * i + r) * 33 + 4 * c4; const float s = nw ? nw[k0 + 8 * i + r] : 1.f; d[0] = v[i].x * s; d[1] = v[i].y * s; d[2] = v[i].z * s; d[3] = v[i].w * s; } }
;     asm volatile("s_waitcnt lgkmcnt(0)" ::: "memory");
;     const int c = lane & 7;
; #pragma unroll
;     for (int j = 0; j < 4; ++j) { const int n = (lane >> 3) + 8 * j; const LAS float* s = scr + (8 * c) * 33 + n;
;         v4u o; o.x = pkbf(s[0 * 33], s[1 * 33]); o.y = pkbf(s[2 * 33], s[3 * 33]); o.z = pkbf(s[4 * 33], s[5 * 33]); o.w = pkbf(s[6 * 33], s[7 * 33]);
;         *(v4u*)(WT + (size_t)(drow0 + n) * K + k0 + 8 * c) = o; }
;     asm volatile("s_waitcnt lgkmcnt(0)" ::: "memory");
; }
; template <int MODE> __device__ __forceinline__ void conv_mat(const float* W, const float* nw, int K, int N, bf16* WT, LAS float* scr, int gw, int NGW, int lane) {
;     const int nblk = N / 32, nitems = (K / 64) * nblk;
;     for (int it = gw; it < nitems; it += NGW) { const int kb = it / nblk, nb = it % nblk, n0 = 32 * nb; int d = n0;
;         if (MODE == 1) { d = (n0 < DFF) ? 256 * (n0 / 128) + (n0 % 128) : 256 * ((n0 - DFF) / 128) + 128 + ((n0 - DFF) % 128); }
;         tr_item(W, nw, K, N, WT, 64 * kb, n0, d, scr, lane); }
; __global__ void __launch_bounds__(512, 2) fwd_megakernel(Args a) {
;     ...
;     conv_mat<0>(a.in[I_WOUT], nullptr, DM, DM, WWO, scr, gw, NGW, lane);
.LBB0_52:
	s_add_u32 s0, s62, 0x7700000
	s_addc_u32 s1, s63, 0
	v_writelane_b32 v250, s0, 32
	s_cmpk_gt_i32 s34, 0x7ff
	s_nop 0
	v_writelane_b32 v250, s1, 33
	s_cbranch_scc1 .Lcv2_done
	v_lshlrev_b32_e32 v148, 4, v225
	v_readlane_b32 s3, v250, 3
	v_mul_u32_u24_e32 v151, 0x84, v224
	v_add_u32_e32 v150, s3, v148
	v_readlane_b32 s0, v250, 32
	v_mov_b32_e32 v149, 0
	v_readlane_b32 s78, v250, 26
	v_readlane_b32 s79, v250, 27
	v_mul_u32_u24_e32 v145, 0x420, v225
	v_readlane_b32 s1, v250, 33
	v_lshlrev_b32_e32 v152, 2, v224
	v_add_u32_e32 v150, v150, v151
	v_lshl_add_u64 v[146:147], s[78:79], 0, v[148:149]
	v_lshl_add_u64 v[148:149], s[0:1], 0, v[148:149]
	v_add3_u32 v145, s3, v145, v152
	s_lshl_b32 s3, s34, 5
	s_lshl_b32 s6, s64, 5
	v_add_u32_e32 v151, 0x420, v150
	v_add_u32_e32 v152, 0x428, v150
	v_add_u32_e32 v153, 0x840, v150
	v_add_u32_e32 v154, 0x848, v150
	v_add_u32_e32 v155, 0xc60, v150
	v_add_u32_e32 v156, 0xc68, v150
	v_add_u32_e32 v157, 0x1080, v150
	v_add_u32_e32 v158, 0x1088, v150
	v_add_u32_e32 v159, 0x14a0, v150
	v_add_u32_e32 v160, 0x14a8, v150
	v_add_u32_e32 v161, 0x18c0, v150
	v_add_u32_e32 v162, 0x18c8, v150
	v_add_u32_e32 v163, 0x1ce0, v150
	v_add_u32_e32 v164, 0x1ce8, v150
	s_mov_b32 s7, s34
	v_readlane_b32 s74, v250, 22
	v_readlane_b32 s75, v250, 23
	v_readlane_b32 s76, v250, 24
	v_readlane_b32 s77, v250, 25
.LBB0_54:
	s_ashr_i32 s0, s7, 31
	s_lshr_b32 s0, s0, 26
	s_add_i32 s0, s7, s0
	s_lshl_b32 s1, s0, 5
	s_andn2_b32 s0, s0, 63
	s_and_b32 s1, s1, 0xfffff800
	v_or_b32_e32 v166, s0, v224
	s_sub_i32 s72, s3, s1
	v_or_b32_e32 v168, 8, v166
	v_or_b32_e32 v170, 16, v166
	v_or_b32_e32 v172, 24, v166
	v_or_b32_e32 v174, 32, v166
	v_or_b32_e32 v176, 40, v166
	v_or_b32_e32 v180, 48, v166
	v_or_b32_e32 v182, 56, v166
	v_ashrrev_i32_e32 v167, 31, v166
	s_ashr_i32 s73, s72, 31
	v_ashrrev_i32_e32 v169, 31, v168
	v_ashrrev_i32_e32 v171, 31, v170
	v_ashrrev_i32_e32 v173, 31, v172
	v_ashrrev_i32_e32 v175, 31, v174
	v_ashrrev_i32_e32 v177, 31, v176
	v_ashrrev_i32_e32 v181, 31, v180
	v_ashrrev_i32_e32 v183, 31, v182
	v_lshlrev_b64 v[166:167], 13, v[166:167]
	v_lshl_add_u64 v[184:185], s[72:73], 2, v[146:147]
	v_lshlrev_b64 v[168:169], 13, v[168:169]
	v_lshlrev_b64 v[170:171], 13, v[170:171]
	v_lshlrev_b64 v[172:173], 13, v[172:173]
	v_lshlrev_b64 v[174:175], 13, v[174:175]
	v_lshlrev_b64 v[176:177], 13, v[176:177]
	v_lshlrev_b64 v[180:181], 13, v[180:181]
	v_lshlrev_b64 v[182:183], 13, v[182:183]
	v_lshl_add_u64 v[166:167], v[184:185], 0, v[166:167]
	v_lshl_add_u64 v[186:187], v[184:185], 0, v[168:169]
	v_lshl_add_u64 v[188:189], v[184:185], 0, v[170:171]
	v_lshl_add_u64 v[190:191], v[184:185], 0, v[172:173]
	v_lshl_add_u64 v[192:193], v[184:185], 0, v[174:175]
	v_lshl_add_u64 v[194:195], v[184:185], 0, v[176:177]
	v_lshl_add_u64 v[196:197], v[184:185], 0, v[180:181]
	v_lshl_add_u64 v[198:199], v[184:185], 0, v[182:183]
	global_load_dwordx4 v[166:169], v[166:167], off nt
	s_nop 0
	global_load_dwordx4 v[170:173], v[186:187], off nt
	global_load_dwordx4 v[174:177], v[188:189], off nt
	global_load_dwordx4 v[180:183], v[190:191], off nt
	s_nop 0
	global_load_dwordx4 v[184:187], v[192:193], off nt
	global_load_dwordx4 v[188:191], v[194:195], off nt
	s_nop 0
	global_load_dwordx4 v[192:195], v[196:197], off nt
	s_nop 0
	global_load_dwordx4 v[196:199], v[198:199], off nt
	v_add_u32_e32 v202, s72, v224
	v_add_u32_e32 v204, 8, v202
	v_add_u32_e32 v206, 16, v202
	v_add_u32_e32 v208, 24, v202
	s_ashr_i32 s1, s0, 31
	v_ashrrev_i32_e32 v203, 31, v202
	v_ashrrev_i32_e32 v205, 31, v204
	v_ashrrev_i32_e32 v207, 31, v206
	v_ashrrev_i32_e32 v209, 31, v208
	v_lshl_add_u64 v[200:201], s[0:1], 1, v[148:149]
	v_lshlrev_b64 v[202:203], 12, v[202:203]
	v_lshlrev_b64 v[204:205], 12, v[204:205]
	v_lshlrev_b64 v[206:207], 12, v[206:207]
	v_lshlrev_b64 v[208:209], 12, v[208:209]
	v_lshl_add_u64 v[202:203], v[200:201], 0, v[202:203]
	v_lshl_add_u64 v[204:205], v[200:201], 0, v[204:205]
	v_lshl_add_u64 v[206:207], v[200:201], 0, v[206:207]
	v_lshl_add_u64 v[200:201], v[200:201], 0, v[208:209]
	s_add_i32 s7, s7, s64
	s_add_i32 s3, s3, s6
	s_cmpk_lt_i32 s7, 0x800
	s_waitcnt vmcnt(7)
	ds_write2_b32 v150, v166, v167 offset1:1
	ds_write2_b32 v150, v168, v169 offset0:2 offset1:3
	s_waitcnt vmcnt(6)
	ds_write2_b32 v151, v170, v171 offset1:1
	ds_write2_b32 v152, v172, v173 offset1:1
	s_waitcnt vmcnt(5)
	ds_write2_b32 v153, v174, v175 offset1:1
	ds_write2_b32 v154, v176, v177 offset1:1
	s_waitcnt vmcnt(4)
	ds_write2_b32 v155, v180, v181 offset1:1
	ds_write2_b32 v156, v182, v183 offset1:1
	s_waitcnt vmcnt(3)
	ds_write2_b32 v157, v184, v185 offset1:1
	ds_write2_b32 v158, v186, v187 offset1:1
	s_waitcnt vmcnt(2)
	ds_write2_b32 v159, v188, v189 offset1:1
	ds_write2_b32 v160, v190, v191 offset1:1
	s_waitcnt vmcnt(1)
	ds_write2_b32 v161, v192, v193 offset1:1
	ds_write2_b32 v162, v194, v195 offset1:1
	s_waitcnt vmcnt(0)
	ds_write2_b32 v163, v196, v197 offset1:1
	ds_write2_b32 v164, v198, v199 offset1:1
	s_waitcnt lgkmcnt(0)
	ds_read2_b32 v[170:171], v145 offset0:33 offset1:41
	ds_read2_b32 v[172:173], v145 offset1:8
	ds_read2_b32 v[174:175], v145 offset0:66 offset1:74
	ds_read2_b32 v[176:177], v145 offset0:99 offset1:107
	ds_read2_b32 v[180:181], v145 offset0:132 offset1:140
	ds_read2_b32 v[182:183], v145 offset0:165 offset1:173
	ds_read2_b32 v[184:185], v145 offset0:198 offset1:206
	ds_read2_b32 v[186:187], v145 offset0:231 offset1:239
	ds_read2_b32 v[188:189], v145 offset0:49 offset1:57
	ds_read2_b32 v[190:191], v145 offset0:16 offset1:24
	ds_read2_b32 v[192:193], v145 offset0:82 offset1:90
	ds_read2_b32 v[194:195], v145 offset0:115 offset1:123
	ds_read2_b32 v[196:197], v145 offset0:148 offset1:156
	ds_read2_b32 v[198:199], v145 offset0:181 offset1:189
	ds_read2_b32 v[208:209], v145 offset0:214 offset1:222
	ds_read2_b32 v[210:211], v145 offset0:247 offset1:255
	s_waitcnt lgkmcnt(14)
	v_cvt_pk_bf16_f32 v166, v172, v170
	s_waitcnt lgkmcnt(12)
	v_cvt_pk_bf16_f32 v167, v174, v176
	s_waitcnt lgkmcnt(10)
	v_cvt_pk_bf16_f32 v168, v180, v182
	s_waitcnt lgkmcnt(8)
	v_cvt_pk_bf16_f32 v169, v184, v186
	v_cvt_pk_bf16_f32 v170, v173, v171
	v_cvt_pk_bf16_f32 v171, v175, v177
	v_cvt_pk_bf16_f32 v172, v181, v183
	v_cvt_pk_bf16_f32 v173, v185, v187
	s_waitcnt lgkmcnt(6)
	v_cvt_pk_bf16_f32 v174, v190, v188
	s_waitcnt lgkmcnt(4)
	v_cvt_pk_bf16_f32 v175, v192, v194
	s_waitcnt lgkmcnt(2)
	v_cvt_pk_bf16_f32 v176, v196, v198
	s_waitcnt lgkmcnt(0)
	v_cvt_pk_bf16_f32 v177, v208, v210
	v_cvt_pk_bf16_f32 v180, v191, v189
	v_cvt_pk_bf16_f32 v181, v193, v195
	v_cvt_pk_bf16_f32 v182, v197, v199
	v_cvt_pk_bf16_f32 v183, v209, v211
	global_store_dwordx4 v[202:203], v[166:169], off
	global_store_dwordx4 v[204:205], v[170:173], off
	global_store_dwordx4 v[206:207], v[174:177], off
	global_store_dwordx4 v[200:201], v[180:183], off
	s_waitcnt lgkmcnt(0)
	s_cbranch_scc1 .LBB0_54
